# prep phase: weight-transposing loops software-pipelined (next tile loads issued before current tile transposed read/store)
# speedup vs baseline: 1.0000x; 1.0000x over previous
; __device__ __forceinline__ u32x4 pack8(const float* v) { u32x4 w; w.x = cvt_pk_bf16(v[0], v[1]); w.y = cvt_pk_bf16(v[2], v[3]); w.z = cvt_pk_bf16(v[4], v[5]); w.w = cvt_pk_bf16(v[6], v[7]); return w; }
; __device__ __forceinline__ void transpose_tile(const float* W, int K, int N, bf16_t* Bt, int ldb, int mode, int tk, int tn, float* tile  ) {
;     const int tid = threadIdx.x;
;     { const int r = tid >> 4, c4 = (tid & 15) * 4;
; #pragma unroll
;       for (int hh = 0; hh < 2; ++hh) { const int rr = r + hh * 32; const f32x4 v = __builtin_nontemporal_load((const f32x4*)(W + (size_t)(tk * 64 + rr) * N + tn * 64 + c4));
;           tile[rr * 65 + c4] = v[0]; tile[rr * 65 + c4 + 1] = v[1]; tile[rr * 65 + c4 + 2] = v[2]; tile[rr * 65 + c4 + 3] = v[3]; } }
;     __syncthreads();
;     { const int n = tid >> 3, k8 = (tid & 7) * 8; float v[8];
; #pragma unroll
;       for (int j = 0; j < 8; ++j) v[j] = tile[(k8 + j) * 65 + n];
;       const int ng = tn * 64 + n; const int row = mode == 0 ? ng : ((ng >> 7) * 256 + (mode - 1) * 128 + (ng & 127));
;       *(u32x4*)(Bt + (size_t)row * ldb + tk * 64 + k8) = pack8(v); }
;     __syncthreads();
; }
; __device__ void phase_prep(const Args& A, float* ldsf) {
;     ...
;     for (int j = 0; j < 7; ++j) { const int ntk = jobs[j].K / 64, ntn = jobs[j].N / 64, ntile = ntk * ntn;
;         for (int t = blockIdx.x; t < ntile; t += gridDim.x) transpose_tile(jobs[j].W, jobs[j].K, jobs[j].N, jobs[j].Bt, jobs[j].ldb, jobs[j].mode, t / ntn, t % ntn, ldsf); }
.LBB0_20:
	s_mul_hi_i32 s10, s9, 0x66666667
	s_lshr_b32 s11, s10, 31
	s_ashr_i32 s10, s10, 6
	s_add_i32 s11, s10, s11
	s_lshl_b32 s10, s11, 6
	s_mulk_i32 s11, 0xd800
	s_add_i32 s12, s3, s11
	s_ashr_i32 s13, s12, 31
	v_or_b32_e32 v22, s10, v8
	v_add_u32_e32 v24, s10, v9
	v_lshl_add_u64 v[20:21], s[12:13], 2, v[2:3]
	v_mad_i64_i32 v[22:23], s[14:15], v22, s0, v[20:21]
	v_mad_i64_i32 v[24:25], s[14:15], v24, s0, v[20:21]
	global_load_dwordx4 v[20:23], v[22:23], off nt
	s_nop 0
	global_load_dwordx4 v[24:27], v[24:25], off nt
	v_add_u32_e32 v28, s12, v10
	v_ashrrev_i32_e32 v29, 31, v28
	v_lshlrev_b64 v[28:29], 12, v[28:29]
	s_ashr_i32 s11, s10, 31
	v_lshl_add_u64 v[28:29], s[76:77], 0, v[28:29]
	s_add_i32 s9, s9, s1
	s_add_i32 s3, s3, s8
	v_lshl_add_u64 v[28:29], s[10:11], 1, v[28:29]
	s_cmpk_gt_i32 s9, 0x13ff
	v_lshl_add_u64 v[28:29], v[28:29], 0, v[0:1]
	s_cselect_b32 s22, 0, 1
	s_waitcnt vmcnt(0)
	s_branch .Ltp0_body
.Ltp0_top:
	s_waitcnt vmcnt(1)
.Ltp0_body:
	ds_write2_b32 v4, v20, v21 offset1:1
	ds_write2_b32 v4, v22, v23 offset0:2 offset1:3
	ds_write2_b32 v5, v24, v25 offset1:1
	ds_write2_b32 v17, v26, v27 offset1:1
	v_mov_b32_e32 v108, v28
	v_mov_b32_e32 v109, v29
	s_waitcnt lgkmcnt(0)
	s_barrier
	s_cmp_lg_u32 s22, 0
	s_cbranch_scc0 .Ltp0_nohead
	s_mul_hi_i32 s10, s9, 0x66666667
	s_lshr_b32 s11, s10, 31
	s_ashr_i32 s10, s10, 6
	s_add_i32 s11, s10, s11
	s_lshl_b32 s10, s11, 6
	s_mulk_i32 s11, 0xd800
	s_add_i32 s12, s3, s11
	s_ashr_i32 s13, s12, 31
	v_or_b32_e32 v22, s10, v8
	v_add_u32_e32 v24, s10, v9
	v_lshl_add_u64 v[20:21], s[12:13], 2, v[2:3]
	v_mad_i64_i32 v[22:23], s[14:15], v22, s0, v[20:21]
	v_mad_i64_i32 v[24:25], s[14:15], v24, s0, v[20:21]
	global_load_dwordx4 v[20:23], v[22:23], off nt
	s_nop 0
	global_load_dwordx4 v[24:27], v[24:25], off nt
	v_add_u32_e32 v28, s12, v10
	v_ashrrev_i32_e32 v29, 31, v28
	v_lshlrev_b64 v[28:29], 12, v[28:29]
	s_ashr_i32 s11, s10, 31
	v_lshl_add_u64 v[28:29], s[76:77], 0, v[28:29]
	s_add_i32 s9, s9, s1
	s_add_i32 s3, s3, s8
	v_lshl_add_u64 v[28:29], s[10:11], 1, v[28:29]
	s_cmpk_gt_i32 s9, 0x13ff
	v_lshl_add_u64 v[28:29], v[28:29], 0, v[0:1]
	s_cselect_b32 s23, 0, 1
	s_branch .Ltp0_tail
.Ltp0_nohead:
	s_mov_b32 s23, 0
.Ltp0_tail:
	ds_read2_b32 v[100:101], v18 offset1:65
	ds_read2_b32 v[102:103], v18 offset0:130 offset1:195
	ds_read2_b32 v[104:105], v19 offset0:4 offset1:69
	ds_read2_b32 v[106:107], v19 offset0:134 offset1:199
	s_waitcnt lgkmcnt(3)
	v_cvt_pk_bf16_f32 v100, v100, v101
	s_waitcnt lgkmcnt(2)
	v_cvt_pk_bf16_f32 v101, v102, v103
	s_waitcnt lgkmcnt(1)
	v_cvt_pk_bf16_f32 v102, v104, v105
	s_waitcnt lgkmcnt(0)
	v_cvt_pk_bf16_f32 v103, v106, v107
	global_store_dwordx4 v[108:109], v[100:103], off
	s_barrier
	s_cmp_lg_u32 s22, 0
	s_mov_b32 s22, s23
	s_cbranch_scc1 .Ltp0_top

; __device__ __forceinline__ u32x4 pack8(const float* v) { u32x4 w; w.x = cvt_pk_bf16(v[0], v[1]); w.y = cvt_pk_bf16(v[2], v[3]); w.z = cvt_pk_bf16(v[4], v[5]); w.w = cvt_pk_bf16(v[6], v[7]); return w; }
; __device__ __forceinline__ void transpose_tile(const float* W, int K, int N, bf16_t* Bt, int ldb, int mode, int tk, int tn, float* tile  ) {
;     ...
;       for (int hh = 0; hh < 2; ++hh) { const int rr = r + hh * 32; const f32x4 v = __builtin_nontemporal_load((const f32x4*)(W + (size_t)(tk * 64 + rr) * N + tn * 64 + c4));
;           tile[rr * 65 + c4] = v[0]; tile[rr * 65 + c4 + 1] = v[1]; tile[rr * 65 + c4 + 2] = v[2]; tile[rr * 65 + c4 + 3] = v[3]; } }
;     __syncthreads();
;     { const int n = tid >> 3, k8 = (tid & 7) * 8; float v[8];
; #pragma unroll
;       for (int j = 0; j < 8; ++j) v[j] = tile[(k8 + j) * 65 + n];
;       const int ng = tn * 64 + n; const int row = mode == 0 ? ng : ((ng >> 7) * 256 + (mode - 1) * 128 + (ng & 127));
;       *(u32x4*)(Bt + (size_t)row * ldb + tk * 64 + k8) = pack8(v); }
; __device__ void phase_prep(const Args& A, float* ldsf) {
;     ...
;         for (int t = blockIdx.x; t < ntile; t += gridDim.x) transpose_tile(jobs[j].W, jobs[j].K, jobs[j].N, jobs[j].Bt, jobs[j].ldb, jobs[j].mode, t / ntn, t % ntn, ldsf); }
.LBB0_23:
	s_ashr_i32 s12, s11, 31
	s_lshr_b32 s12, s12, 27
	s_add_i32 s12, s11, s12
	s_ashr_i32 s13, s12, 5
	s_lshl_b32 s12, s13, 6
	s_lshl_b32 s13, s13, 11
	s_sub_i32 s14, s10, s13
	v_or_b32_e32 v22, s12, v8
	v_add_u32_e32 v24, s12, v9
	s_ashr_i32 s15, s14, 31
	v_ashrrev_i32_e32 v23, 31, v22
	v_ashrrev_i32_e32 v25, 31, v24
	v_lshl_add_u64 v[26:27], s[14:15], 2, v[4:5]
	v_lshlrev_b64 v[22:23], 13, v[22:23]
	v_lshlrev_b64 v[24:25], 13, v[24:25]
	v_lshl_add_u64 v[22:23], v[26:27], 0, v[22:23]
	v_lshl_add_u64 v[26:27], v[26:27], 0, v[24:25]
	global_load_dwordx4 v[22:25], v[22:23], off nt
	s_nop 0
	global_load_dwordx4 v[26:29], v[26:27], off nt
	v_add_u32_e32 v30, s14, v10
	v_ashrrev_i32_e32 v31, 31, v30
	v_lshlrev_b64 v[30:31], 12, v[30:31]
	s_ashr_i32 s13, s12, 31
	v_lshl_add_u64 v[30:31], s[0:1], 0, v[30:31]
	s_add_i32 s11, s11, s3
	s_add_i32 s10, s10, s9
	v_lshl_add_u64 v[30:31], s[12:13], 1, v[30:31]
	s_cmpk_lt_i32 s11, 0x200
	v_lshl_add_u64 v[30:31], v[30:31], 0, v[0:1]
	s_cselect_b32 s22, 1, 0
	s_waitcnt vmcnt(0)
	s_branch .Ltp1_body

; __device__ __forceinline__ u32x4 pack8(const float* v) { u32x4 w; w.x = cvt_pk_bf16(v[0], v[1]); w.y = cvt_pk_bf16(v[2], v[3]); w.z = cvt_pk_bf16(v[4], v[5]); w.w = cvt_pk_bf16(v[6], v[7]); return w; }
; __device__ __forceinline__ void transpose_tile(const float* W, int K, int N, bf16_t* Bt, int ldb, int mode, int tk, int tn, float* tile  ) {
;     ...
;       for (int hh = 0; hh < 2; ++hh) { const int rr = r + hh * 32; const f32x4 v = __builtin_nontemporal_load((const f32x4*)(W + (size_t)(tk * 64 + rr) * N + tn * 64 + c4));
;           tile[rr * 65 + c4] = v[0]; tile[rr * 65 + c4 + 1] = v[1]; tile[rr * 65 + c4 + 2] = v[2]; tile[rr * 65 + c4 + 3] = v[3]; } }
;     __syncthreads();
;     { const int n = tid >> 3, k8 = (tid & 7) * 8; float v[8];
; #pragma unroll
;       for (int j = 0; j < 8; ++j) v[j] = tile[(k8 + j) * 65 + n];
;       const int ng = tn * 64 + n; const int row = mode == 0 ? ng : ((ng >> 7) * 256 + (mode - 1) * 128 + (ng & 127));
;       *(u32x4*)(Bt + (size_t)row * ldb + tk * 64 + k8) = pack8(v); }
; __device__ void phase_prep(const Args& A, float* ldsf) {
;     ...
;         for (int t = blockIdx.x; t < ntile; t += gridDim.x) transpose_tile(jobs[j].W, jobs[j].K, jobs[j].N, jobs[j].Bt, jobs[j].ldb, jobs[j].mode, t / ntn, t % ntn, ldsf); }
.Ltp1_body:
	ds_write2_b32 v17, v22, v23 offset1:1
	ds_write2_b32 v17, v24, v25 offset0:2 offset1:3
	ds_write2_b32 v19, v26, v27 offset1:1
	ds_write2_b32 v20, v28, v29 offset1:1
	v_mov_b32_e32 v108, v30
	v_mov_b32_e32 v109, v31
	s_waitcnt lgkmcnt(0)
	s_barrier
	s_cmp_lg_u32 s22, 0
	s_cbranch_scc0 .Ltp1_nohead
	s_ashr_i32 s12, s11, 31
	s_lshr_b32 s12, s12, 27
	s_add_i32 s12, s11, s12
	s_ashr_i32 s13, s12, 5
	s_lshl_b32 s12, s13, 6
	s_lshl_b32 s13, s13, 11
	s_sub_i32 s14, s10, s13
	v_or_b32_e32 v22, s12, v8
	v_add_u32_e32 v24, s12, v9
	s_ashr_i32 s15, s14, 31
	v_ashrrev_i32_e32 v23, 31, v22
	v_ashrrev_i32_e32 v25, 31, v24
	v_lshl_add_u64 v[26:27], s[14:15], 2, v[4:5]
	v_lshlrev_b64 v[22:23], 13, v[22:23]
	v_lshlrev_b64 v[24:25], 13, v[24:25]
	v_lshl_add_u64 v[22:23], v[26:27], 0, v[22:23]
	v_lshl_add_u64 v[26:27], v[26:27], 0, v[24:25]
	global_load_dwordx4 v[22:25], v[22:23], off nt
	s_nop 0
	global_load_dwordx4 v[26:29], v[26:27], off nt
	v_add_u32_e32 v30, s14, v10
	v_ashrrev_i32_e32 v31, 31, v30
	v_lshlrev_b64 v[30:31], 12, v[30:31]
	s_ashr_i32 s13, s12, 31
	v_lshl_add_u64 v[30:31], s[0:1], 0, v[30:31]
	s_add_i32 s11, s11, s3
	s_add_i32 s10, s10, s9
	v_lshl_add_u64 v[30:31], s[12:13], 1, v[30:31]
	s_cmpk_lt_i32 s11, 0x200
	v_lshl_add_u64 v[30:31], v[30:31], 0, v[0:1]
	s_cselect_b32 s23, 1, 0
	s_branch .Ltp1_tail

; __device__ __forceinline__ u32x4 pack8(const float* v) { u32x4 w; w.x = cvt_pk_bf16(v[0], v[1]); w.y = cvt_pk_bf16(v[2], v[3]); w.z = cvt_pk_bf16(v[4], v[5]); w.w = cvt_pk_bf16(v[6], v[7]); return w; }
; __device__ __forceinline__ void transpose_tile(const float* W, int K, int N, bf16_t* Bt, int ldb, int mode, int tk, int tn, float* tile  ) {
;     ...
;     __syncthreads();
;     { const int n = tid >> 3, k8 = (tid & 7) * 8; float v[8];
; #pragma unroll
;       for (int j = 0; j < 8; ++j) v[j] = tile[(k8 + j) * 65 + n];
;       const int ng = tn * 64 + n; const int row = mode == 0 ? ng : ((ng >> 7) * 256 + (mode - 1) * 128 + (ng & 127));
;       *(u32x4*)(Bt + (size_t)row * ldb + tk * 64 + k8) = pack8(v); }
; __device__ void phase_prep(const Args& A, float* ldsf) {
;     ...
;     for (int j = 0; j < 7; ++j) { const int ntk = jobs[j].K / 64, ntn = jobs[j].N / 64, ntile = ntk * ntn;
;         for (int t = blockIdx.x; t < ntile; t += gridDim.x) transpose_tile(jobs[j].W, jobs[j].K, jobs[j].N, jobs[j].Bt, jobs[j].ldb, jobs[j].mode, t / ntn, t % ntn, ldsf); }
.Ltp1_tail:
	ds_read2_b32 v[100:101], v18 offset1:65
	ds_read2_b32 v[102:103], v18 offset0:130 offset1:195
	ds_read2_b32 v[104:105], v3 offset0:4 offset1:69
	ds_read2_b32 v[106:107], v3 offset0:134 offset1:199
	s_waitcnt lgkmcnt(3)
	v_cvt_pk_bf16_f32 v100, v100, v101
	s_waitcnt lgkmcnt(2)
	v_cvt_pk_bf16_f32 v101, v102, v103
	s_waitcnt lgkmcnt(1)
	v_cvt_pk_bf16_f32 v102, v104, v105
	s_waitcnt lgkmcnt(0)
	v_cvt_pk_bf16_f32 v103, v106, v107
	global_store_dwordx4 v[108:109], v[100:103], off
	s_barrier
	s_cmp_lg_u32 s22, 0
	s_mov_b32 s22, s23
	s_cbranch_scc1 .Ltp1_top
	s_add_u32 s0, s76, 0x2800800
	v_mov_b32_e32 v3, 0
	s_addc_u32 s1, s77, 0
	v_lshl_add_u64 v[4:5], s[62:63], 0, v[2:3]
	v_add_u32_e32 v2, 0x2080, v17
	v_add_u32_e32 v19, 0x2088, v17
	v_mov_b32_e32 v1, v3
	v_add_u32_e32 v3, 0x400, v18
	s_mov_b32 s10, s2
.LBB0_25:
	s_ashr_i32 s11, s10, 31
	s_lshr_b32 s11, s11, 27
	s_add_i32 s11, s10, s11
	s_ashr_i32 s11, s11, 5
	s_lshl_b32 s12, s11, 6
	s_lshl_b32 s11, s11, 11
	s_sub_i32 s14, s8, s11
	v_or_b32_e32 v20, s12, v8
	v_add_u32_e32 v22, s12, v9
	s_ashr_i32 s15, s14, 31
	v_ashrrev_i32_e32 v21, 31, v20
	v_ashrrev_i32_e32 v23, 31, v22
	v_lshl_add_u64 v[24:25], s[14:15], 2, v[4:5]
	v_lshlrev_b64 v[20:21], 13, v[20:21]
	v_lshlrev_b64 v[22:23], 13, v[22:23]
	v_lshl_add_u64 v[20:21], v[24:25], 0, v[20:21]
	v_lshl_add_u64 v[24:25], v[24:25], 0, v[22:23]
	global_load_dwordx4 v[20:23], v[20:21], off nt
	s_nop 0
	global_load_dwordx4 v[24:27], v[24:25], off nt
	v_add_u32_e32 v28, s14, v10
	v_ashrrev_i32_e32 v29, 31, v28
	v_lshlrev_b64 v[28:29], 12, v[28:29]
	s_ashr_i32 s13, s12, 31
	v_lshl_add_u64 v[28:29], s[0:1], 0, v[28:29]
	s_add_i32 s10, s10, s3
	s_add_i32 s8, s8, s9
	v_lshl_add_u64 v[28:29], s[12:13], 1, v[28:29]
	s_cmpk_lt_i32 s10, 0x200
	v_lshl_add_u64 v[28:29], v[28:29], 0, v[0:1]
	s_cselect_b32 s22, 1, 0
	s_waitcnt vmcnt(0)
	s_branch .Ltp2_body

; __device__ __forceinline__ u32x4 pack8(const float* v) { u32x4 w; w.x = cvt_pk_bf16(v[0], v[1]); w.y = cvt_pk_bf16(v[2], v[3]); w.z = cvt_pk_bf16(v[4], v[5]); w.w = cvt_pk_bf16(v[6], v[7]); return w; }
; __device__ __forceinline__ void transpose_tile(const float* W, int K, int N, bf16_t* Bt, int ldb, int mode, int tk, int tn, float* tile  ) {
;     ...
;       for (int hh = 0; hh < 2; ++hh) { const int rr = r + hh * 32; const f32x4 v = __builtin_nontemporal_load((const f32x4*)(W + (size_t)(tk * 64 + rr) * N + tn * 64 + c4));
;           tile[rr * 65 + c4] = v[0]; tile[rr * 65 + c4 + 1] = v[1]; tile[rr * 65 + c4 + 2] = v[2]; tile[rr * 65 + c4 + 3] = v[3]; } }
;     __syncthreads();
;     { const int n = tid >> 3, k8 = (tid & 7) * 8; float v[8];
; #pragma unroll
;       for (int j = 0; j < 8; ++j) v[j] = tile[(k8 + j) * 65 + n];
;       const int ng = tn * 64 + n; const int row = mode == 0 ? ng : ((ng >> 7) * 256 + (mode - 1) * 128 + (ng & 127));
;       *(u32x4*)(Bt + (size_t)row * ldb + tk * 64 + k8) = pack8(v); }
; __device__ void phase_prep(const Args& A, float* ldsf) {
;     ...
;         for (int t = blockIdx.x; t < ntile; t += gridDim.x) transpose_tile(jobs[j].W, jobs[j].K, jobs[j].N, jobs[j].Bt, jobs[j].ldb, jobs[j].mode, t / ntn, t % ntn, ldsf); }
.Ltp2_body:
	ds_write2_b32 v17, v20, v21 offset1:1
	ds_write2_b32 v17, v22, v23 offset0:2 offset1:3
	ds_write2_b32 v2, v24, v25 offset1:1
	ds_write2_b32 v19, v26, v27 offset1:1
	v_mov_b32_e32 v108, v28
	v_mov_b32_e32 v109, v29
	s_waitcnt lgkmcnt(0)
	s_barrier
	s_cmp_lg_u32 s22, 0
	s_cbranch_scc0 .Ltp2_nohead
	s_ashr_i32 s11, s10, 31
	s_lshr_b32 s11, s11, 27
	s_add_i32 s11, s10, s11
	s_ashr_i32 s11, s11, 5
	s_lshl_b32 s12, s11, 6
	s_lshl_b32 s11, s11, 11
	s_sub_i32 s14, s8, s11
	v_or_b32_e32 v20, s12, v8
	v_add_u32_e32 v22, s12, v9
	s_ashr_i32 s15, s14, 31
	v_ashrrev_i32_e32 v21, 31, v20
	v_ashrrev_i32_e32 v23, 31, v22
	v_lshl_add_u64 v[24:25], s[14:15], 2, v[4:5]
	v_lshlrev_b64 v[20:21], 13, v[20:21]
	v_lshlrev_b64 v[22:23], 13, v[22:23]
	v_lshl_add_u64 v[20:21], v[24:25], 0, v[20:21]
	v_lshl_add_u64 v[24:25], v[24:25], 0, v[22:23]
	global_load_dwordx4 v[20:23], v[20:21], off nt
	s_nop 0
	global_load_dwordx4 v[24:27], v[24:25], off nt
	v_add_u32_e32 v28, s14, v10
	v_ashrrev_i32_e32 v29, 31, v28
	v_lshlrev_b64 v[28:29], 12, v[28:29]
	s_ashr_i32 s13, s12, 31
	v_lshl_add_u64 v[28:29], s[0:1], 0, v[28:29]
	s_add_i32 s10, s10, s3
	s_add_i32 s8, s8, s9
	v_lshl_add_u64 v[28:29], s[12:13], 1, v[28:29]
	s_cmpk_lt_i32 s10, 0x200
	v_lshl_add_u64 v[28:29], v[28:29], 0, v[0:1]
	s_cselect_b32 s23, 1, 0
	s_branch .Ltp2_tail

; __device__ __forceinline__ u32x4 pack8(const float* v) { u32x4 w; w.x = cvt_pk_bf16(v[0], v[1]); w.y = cvt_pk_bf16(v[2], v[3]); w.z = cvt_pk_bf16(v[4], v[5]); w.w = cvt_pk_bf16(v[6], v[7]); return w; }
; __device__ __forceinline__ void transpose_tile(const float* W, int K, int N, bf16_t* Bt, int ldb, int mode, int tk, int tn, float* tile  ) {
;     ...
;     __syncthreads();
;     { const int n = tid >> 3, k8 = (tid & 7) * 8; float v[8];
; #pragma unroll
;       for (int j = 0; j < 8; ++j) v[j] = tile[(k8 + j) * 65 + n];
;       const int ng = tn * 64 + n; const int row = mode == 0 ? ng : ((ng >> 7) * 256 + (mode - 1) * 128 + (ng & 127));
;       *(u32x4*)(Bt + (size_t)row * ldb + tk * 64 + k8) = pack8(v); }
; __device__ void phase_prep(const Args& A, float* ldsf) {
;     ...
;     for (int j = 0; j < 7; ++j) { const int ntk = jobs[j].K / 64, ntn = jobs[j].N / 64, ntile = ntk * ntn;
;         for (int t = blockIdx.x; t < ntile; t += gridDim.x) transpose_tile(jobs[j].W, jobs[j].K, jobs[j].N, jobs[j].Bt, jobs[j].ldb, jobs[j].mode, t / ntn, t % ntn, ldsf); }
.Ltp2_tail:
	ds_read2_b32 v[100:101], v18 offset1:65
	ds_read2_b32 v[102:103], v18 offset0:130 offset1:195
	ds_read2_b32 v[104:105], v3 offset0:4 offset1:69
	ds_read2_b32 v[106:107], v3 offset0:134 offset1:199
	s_waitcnt lgkmcnt(3)
	v_cvt_pk_bf16_f32 v100, v100, v101
	s_waitcnt lgkmcnt(2)
	v_cvt_pk_bf16_f32 v101, v102, v103
	s_waitcnt lgkmcnt(1)
	v_cvt_pk_bf16_f32 v102, v104, v105
	s_waitcnt lgkmcnt(0)
	v_cvt_pk_bf16_f32 v103, v106, v107
	global_store_dwordx4 v[108:109], v[100:103], off
	s_barrier
	s_cmp_lg_u32 s22, 0
	s_mov_b32 s22, s23
	s_cbranch_scc1 .Ltp2_top

; __device__ __forceinline__ u32x4 pack8(const float* v) { u32x4 w; w.x = cvt_pk_bf16(v[0], v[1]); w.y = cvt_pk_bf16(v[2], v[3]); w.z = cvt_pk_bf16(v[4], v[5]); w.w = cvt_pk_bf16(v[6], v[7]); return w; }
; __device__ __forceinline__ void transpose_tile(const float* W, int K, int N, bf16_t* Bt, int ldb, int mode, int tk, int tn, float* tile  ) {
;     ...
;       for (int hh = 0; hh < 2; ++hh) { const int rr = r + hh * 32; const f32x4 v = __builtin_nontemporal_load((const f32x4*)(W + (size_t)(tk * 64 + rr) * N + tn * 64 + c4));
;           tile[rr * 65 + c4] = v[0]; tile[rr * 65 + c4 + 1] = v[1]; tile[rr * 65 + c4 + 2] = v[2]; tile[rr * 65 + c4 + 3] = v[3]; } }
;     __syncthreads();
;     { const int n = tid >> 3, k8 = (tid & 7) * 8; float v[8];
; #pragma unroll
;       for (int j = 0; j < 8; ++j) v[j] = tile[(k8 + j) * 65 + n];
;       const int ng = tn * 64 + n; const int row = mode == 0 ? ng : ((ng >> 7) * 256 + (mode - 1) * 128 + (ng & 127));
;       *(u32x4*)(Bt + (size_t)row * ldb + tk * 64 + k8) = pack8(v); }
; __device__ void phase_prep(const Args& A, float* ldsf) {
;     ...
;         for (int t = blockIdx.x; t < ntile; t += gridDim.x) transpose_tile(jobs[j].W, jobs[j].K, jobs[j].N, jobs[j].Bt, jobs[j].ldb, jobs[j].mode, t / ntn, t % ntn, ldsf); }
.LBB0_28:
	s_ashr_i32 s11, s10, 31
	s_lshr_b32 s11, s11, 27
	s_add_i32 s11, s10, s11
	s_ashr_i32 s11, s11, 5
	s_lshl_b32 s12, s11, 6
	s_lshl_b32 s11, s11, 11
	s_sub_i32 s14, s8, s11
	v_or_b32_e32 v20, s12, v8
	v_add_u32_e32 v22, s12, v9
	s_ashr_i32 s15, s14, 31
	v_ashrrev_i32_e32 v21, 31, v20
	v_ashrrev_i32_e32 v23, 31, v22
	v_lshl_add_u64 v[24:25], s[14:15], 2, v[2:3]
	v_lshlrev_b64 v[20:21], 13, v[20:21]
	v_lshlrev_b64 v[22:23], 13, v[22:23]
	v_lshl_add_u64 v[20:21], v[24:25], 0, v[20:21]
	v_lshl_add_u64 v[24:25], v[24:25], 0, v[22:23]
	global_load_dwordx4 v[20:23], v[20:21], off nt
	s_nop 0
	global_load_dwordx4 v[24:27], v[24:25], off nt
	v_add_u32_e32 v28, s14, v10
	v_ashrrev_i32_e32 v29, 31, v28
	v_lshlrev_b64 v[28:29], 12, v[28:29]
	s_ashr_i32 s13, s12, 31
	v_lshl_add_u64 v[28:29], s[0:1], 0, v[28:29]
	s_add_i32 s10, s10, s3
	s_add_i32 s8, s8, s9
	v_lshl_add_u64 v[28:29], s[12:13], 1, v[28:29]
	s_cmpk_lt_i32 s10, 0x400
	v_lshl_add_u64 v[28:29], v[28:29], 0, v[0:1]
	s_cselect_b32 s22, 1, 0
	s_waitcnt vmcnt(0)
	s_branch .Ltp3_body

; __device__ __forceinline__ u32x4 pack8(const float* v) { u32x4 w; w.x = cvt_pk_bf16(v[0], v[1]); w.y = cvt_pk_bf16(v[2], v[3]); w.z = cvt_pk_bf16(v[4], v[5]); w.w = cvt_pk_bf16(v[6], v[7]); return w; }
; __device__ __forceinline__ void transpose_tile(const float* W, int K, int N, bf16_t* Bt, int ldb, int mode, int tk, int tn, float* tile  ) {
;     ...
;       for (int hh = 0; hh < 2; ++hh) { const int rr = r + hh * 32; const f32x4 v = __builtin_nontemporal_load((const f32x4*)(W + (size_t)(tk * 64 + rr) * N + tn * 64 + c4));
;           tile[rr * 65 + c4] = v[0]; tile[rr * 65 + c4 + 1] = v[1]; tile[rr * 65 + c4 + 2] = v[2]; tile[rr * 65 + c4 + 3] = v[3]; } }
;     __syncthreads();
;     { const int n = tid >> 3, k8 = (tid & 7) * 8; float v[8];
; #pragma unroll
;       for (int j = 0; j < 8; ++j) v[j] = tile[(k8 + j) * 65 + n];
;       const int ng = tn * 64 + n; const int row = mode == 0 ? ng : ((ng >> 7) * 256 + (mode - 1) * 128 + (ng & 127));
;       *(u32x4*)(Bt + (size_t)row * ldb + tk * 64 + k8) = pack8(v); }
; __device__ void phase_prep(const Args& A, float* ldsf) {
;     ...
;         for (int t = blockIdx.x; t < ntile; t += gridDim.x) transpose_tile(jobs[j].W, jobs[j].K, jobs[j].N, jobs[j].Bt, jobs[j].ldb, jobs[j].mode, t / ntn, t % ntn, ldsf); }
.Ltp3_body:
	ds_write2_b32 v4, v20, v21 offset1:1
	ds_write2_b32 v4, v22, v23 offset0:2 offset1:3
	ds_write2_b32 v5, v24, v25 offset1:1
	ds_write2_b32 v17, v26, v27 offset1:1
	v_mov_b32_e32 v108, v28
	v_mov_b32_e32 v109, v29
	s_waitcnt lgkmcnt(0)
	s_barrier
	s_cmp_lg_u32 s22, 0
	s_cbranch_scc0 .Ltp3_nohead
	s_ashr_i32 s11, s10, 31
	s_lshr_b32 s11, s11, 27
	s_add_i32 s11, s10, s11
	s_ashr_i32 s11, s11, 5
	s_lshl_b32 s12, s11, 6
	s_lshl_b32 s11, s11, 11
	s_sub_i32 s14, s8, s11
	v_or_b32_e32 v20, s12, v8
	v_add_u32_e32 v22, s12, v9
	s_ashr_i32 s15, s14, 31
	v_ashrrev_i32_e32 v21, 31, v20
	v_ashrrev_i32_e32 v23, 31, v22
	v_lshl_add_u64 v[24:25], s[14:15], 2, v[2:3]
	v_lshlrev_b64 v[20:21], 13, v[20:21]
	v_lshlrev_b64 v[22:23], 13, v[22:23]
	v_lshl_add_u64 v[20:21], v[24:25], 0, v[20:21]
	v_lshl_add_u64 v[24:25], v[24:25], 0, v[22:23]
	global_load_dwordx4 v[20:23], v[20:21], off nt
	s_nop 0
	global_load_dwordx4 v[24:27], v[24:25], off nt
	v_add_u32_e32 v28, s14, v10
	v_ashrrev_i32_e32 v29, 31, v28
	v_lshlrev_b64 v[28:29], 12, v[28:29]
	s_ashr_i32 s13, s12, 31
	v_lshl_add_u64 v[28:29], s[0:1], 0, v[28:29]
	s_add_i32 s10, s10, s3
	s_add_i32 s8, s8, s9
	v_lshl_add_u64 v[28:29], s[12:13], 1, v[28:29]
	s_cmpk_lt_i32 s10, 0x400
	v_lshl_add_u64 v[28:29], v[28:29], 0, v[0:1]
	s_cselect_b32 s23, 1, 0
	s_branch .Ltp3_tail

; __device__ __forceinline__ u32x4 pack8(const float* v) { u32x4 w; w.x = cvt_pk_bf16(v[0], v[1]); w.y = cvt_pk_bf16(v[2], v[3]); w.z = cvt_pk_bf16(v[4], v[5]); w.w = cvt_pk_bf16(v[6], v[7]); return w; }
; __device__ __forceinline__ void transpose_tile(const float* W, int K, int N, bf16_t* Bt, int ldb, int mode, int tk, int tn, float* tile  ) {
;     ...
;       for (int hh = 0; hh < 2; ++hh) { const int rr = r + hh * 32; const f32x4 v = __builtin_nontemporal_load((const f32x4*)(W + (size_t)(tk * 64 + rr) * N + tn * 64 + c4));
;           tile[rr * 65 + c4] = v[0]; tile[rr * 65 + c4 + 1] = v[1]; tile[rr * 65 + c4 + 2] = v[2]; tile[rr * 65 + c4 + 3] = v[3]; } }
;     __syncthreads();
;     { const int n = tid >> 3, k8 = (tid & 7) * 8; float v[8];
; #pragma unroll
;       for (int j = 0; j < 8; ++j) v[j] = tile[(k8 + j) * 65 + n];
;       const int ng = tn * 64 + n; const int row = mode == 0 ? ng : ((ng >> 7) * 256 + (mode - 1) * 128 + (ng & 127));
;       *(u32x4*)(Bt + (size_t)row * ldb + tk * 64 + k8) = pack8(v); }
; __device__ void phase_prep(const Args& A, float* ldsf) {
;     ...
;         for (int t = blockIdx.x; t < ntile; t += gridDim.x) transpose_tile(jobs[j].W, jobs[j].K, jobs[j].N, jobs[j].Bt, jobs[j].ldb, jobs[j].mode, t / ntn, t % ntn, ldsf); }
.LBB0_31:
	s_mul_hi_i32 s15, s14, 0x2e8ba2e9
	s_lshr_b32 s16, s15, 31
	s_ashr_i32 s15, s15, 4
	s_add_i32 s15, s15, s16
	s_mul_i32 s17, s15, 0xffffea00
	s_add_i32 s18, s13, s17
	s_lshl_b32 s16, s15, 6
	s_ashr_i32 s19, s18, 31
	v_or_b32_e32 v19, s16, v8
	v_lshl_add_u64 v[14:15], s[18:19], 2, v[4:5]
	v_add_u32_e32 v22, s16, v9
	v_mad_i64_i32 v[20:21], s[20:21], v19, s11, v[14:15]
	v_mad_i64_i32 v[14:15], s[20:21], v22, s11, v[14:15]
	global_load_dwordx4 v[20:23], v[20:21], off nt
	s_nop 0
	global_load_dwordx4 v[24:27], v[14:15], off nt
	s_mulk_i32 s15, 0xd400
	v_add_u32_e32 v15, s18, v10
	v_add_u32_e32 v14, s15, v12
	v_and_b32_e32 v15, 0x7f, v15
	v_and_or_b32 v14, v14, s12, v15
	v_ashrrev_i32_e32 v15, 31, v14
	v_lshlrev_b64 v[14:15], 12, v[14:15]
	s_ashr_i32 s17, s16, 31
	v_lshl_add_u64 v[14:15], s[0:1], 0, v[14:15]
	s_add_i32 s14, s14, s3
	s_add_i32 s13, s13, s9
	v_lshl_add_u64 v[14:15], s[16:17], 1, v[14:15]
	v_add_u32_e32 v12, s10, v12
	s_cmpk_lt_i32 s14, 0xb00
	v_lshl_add_u64 v[14:15], v[14:15], 0, v[0:1]
	s_cselect_b32 s22, 1, 0
	s_waitcnt vmcnt(0)
	s_branch .Ltp4_body

; __device__ __forceinline__ u32x4 pack8(const float* v) { u32x4 w; w.x = cvt_pk_bf16(v[0], v[1]); w.y = cvt_pk_bf16(v[2], v[3]); w.z = cvt_pk_bf16(v[4], v[5]); w.w = cvt_pk_bf16(v[6], v[7]); return w; }
; __device__ __forceinline__ void transpose_tile(const float* W, int K, int N, bf16_t* Bt, int ldb, int mode, int tk, int tn, float* tile  ) {
;     ...
;       for (int hh = 0; hh < 2; ++hh) { const int rr = r + hh * 32; const f32x4 v = __builtin_nontemporal_load((const f32x4*)(W + (size_t)(tk * 64 + rr) * N + tn * 64 + c4));
;           tile[rr * 65 + c4] = v[0]; tile[rr * 65 + c4 + 1] = v[1]; tile[rr * 65 + c4 + 2] = v[2]; tile[rr * 65 + c4 + 3] = v[3]; } }
;     __syncthreads();
;     { const int n = tid >> 3, k8 = (tid & 7) * 8; float v[8];
; #pragma unroll
;       for (int j = 0; j < 8; ++j) v[j] = tile[(k8 + j) * 65 + n];
;       const int ng = tn * 64 + n; const int row = mode == 0 ? ng : ((ng >> 7) * 256 + (mode - 1) * 128 + (ng & 127));
;       *(u32x4*)(Bt + (size_t)row * ldb + tk * 64 + k8) = pack8(v); }
; __device__ void phase_prep(const Args& A, float* ldsf) {
;     ...
;         for (int t = blockIdx.x; t < ntile; t += gridDim.x) transpose_tile(jobs[j].W, jobs[j].K, jobs[j].N, jobs[j].Bt, jobs[j].ldb, jobs[j].mode, t / ntn, t % ntn, ldsf); }
.Ltp4_body:
	ds_write2_b32 v11, v20, v21 offset1:1
	ds_write2_b32 v11, v22, v23 offset0:2 offset1:3
	ds_write2_b32 v17, v24, v25 offset1:1
	ds_write2_b32 v18, v26, v27 offset1:1
	v_mov_b32_e32 v108, v14
	v_mov_b32_e32 v109, v15
	s_waitcnt lgkmcnt(0)
	s_barrier
	s_cmp_lg_u32 s22, 0
	s_cbranch_scc0 .Ltp4_nohead
	s_mul_hi_i32 s15, s14, 0x2e8ba2e9
	s_lshr_b32 s16, s15, 31
	s_ashr_i32 s15, s15, 4
	s_add_i32 s15, s15, s16
	s_mul_i32 s17, s15, 0xffffea00
	s_add_i32 s18, s13, s17
	s_lshl_b32 s16, s15, 6
	s_ashr_i32 s19, s18, 31
	v_or_b32_e32 v19, s16, v8
	v_lshl_add_u64 v[14:15], s[18:19], 2, v[4:5]
	v_add_u32_e32 v22, s16, v9
	v_mad_i64_i32 v[20:21], s[20:21], v19, s11, v[14:15]
	v_mad_i64_i32 v[14:15], s[20:21], v22, s11, v[14:15]
	global_load_dwordx4 v[20:23], v[20:21], off nt
	s_nop 0
	global_load_dwordx4 v[24:27], v[14:15], off nt
	s_mulk_i32 s15, 0xd400
	v_add_u32_e32 v15, s18, v10
	v_add_u32_e32 v14, s15, v12
	v_and_b32_e32 v15, 0x7f, v15
	v_and_or_b32 v14, v14, s12, v15
	v_ashrrev_i32_e32 v15, 31, v14
	v_lshlrev_b64 v[14:15], 12, v[14:15]
	s_ashr_i32 s17, s16, 31
	v_lshl_add_u64 v[14:15], s[0:1], 0, v[14:15]
	s_add_i32 s14, s14, s3
	s_add_i32 s13, s13, s9
	v_lshl_add_u64 v[14:15], s[16:17], 1, v[14:15]
	v_add_u32_e32 v12, s10, v12
	s_cmpk_lt_i32 s14, 0xb00
	v_lshl_add_u64 v[14:15], v[14:15], 0, v[0:1]
	s_cselect_b32 s23, 1, 0
	s_branch .Ltp4_tail

; __device__ __forceinline__ u32x4 pack8(const float* v) { u32x4 w; w.x = cvt_pk_bf16(v[0], v[1]); w.y = cvt_pk_bf16(v[2], v[3]); w.z = cvt_pk_bf16(v[4], v[5]); w.w = cvt_pk_bf16(v[6], v[7]); return w; }
; __device__ __forceinline__ void transpose_tile(const float* W, int K, int N, bf16_t* Bt, int ldb, int mode, int tk, int tn, float* tile  ) {
;     ...
;     __syncthreads();
;     { const int n = tid >> 3, k8 = (tid & 7) * 8; float v[8];
; #pragma unroll
;       for (int j = 0; j < 8; ++j) v[j] = tile[(k8 + j) * 65 + n];
;       const int ng = tn * 64 + n; const int row = mode == 0 ? ng : ((ng >> 7) * 256 + (mode - 1) * 128 + (ng & 127));
;       *(u32x4*)(Bt + (size_t)row * ldb + tk * 64 + k8) = pack8(v); }
; __device__ void phase_prep(const Args& A, float* ldsf) {
;     ...
;     for (int j = 0; j < 7; ++j) { const int ntk = jobs[j].K / 64, ntn = jobs[j].N / 64, ntile = ntk * ntn;
;         for (int t = blockIdx.x; t < ntile; t += gridDim.x) transpose_tile(jobs[j].W, jobs[j].K, jobs[j].N, jobs[j].Bt, jobs[j].ldb, jobs[j].mode, t / ntn, t % ntn, ldsf); }
.Ltp4_tail:
	ds_read2_b32 v[100:101], v13 offset1:65
	ds_read2_b32 v[102:103], v13 offset0:130 offset1:195
	ds_read2_b32 v[104:105], v3 offset0:4 offset1:69
	ds_read2_b32 v[106:107], v3 offset0:134 offset1:199
	s_waitcnt lgkmcnt(3)
	v_cvt_pk_bf16_f32 v100, v100, v101
	s_waitcnt lgkmcnt(2)
	v_cvt_pk_bf16_f32 v101, v102, v103
	s_waitcnt lgkmcnt(1)
	v_cvt_pk_bf16_f32 v102, v104, v105
	s_waitcnt lgkmcnt(0)
	v_cvt_pk_bf16_f32 v103, v106, v107
	global_store_dwordx4 v[108:109], v[100:103], off
	s_barrier
	s_cmp_lg_u32 s22, 0
	s_mov_b32 s22, s23
	s_cbranch_scc1 .Ltp4_top
	v_mov_b32_e32 v3, 0
	v_lshl_add_u64 v[4:5], s[70:71], 0, v[2:3]
	s_movk_i32 s11, 0x5800
	v_add_u32_e32 v12, 0x2080, v11
	v_add_u32_e32 v14, 0x2088, v11
	s_movk_i32 s12, 0x80
	v_mov_b32_e32 v1, v3
	v_add_u32_e32 v3, 0x400, v13
	s_mov_b32 s13, s8
	s_mov_b32 s14, s2
.LBB0_33:
	s_mul_hi_i32 s15, s14, 0x2e8ba2e9
	s_lshr_b32 s16, s15, 31
	s_ashr_i32 s15, s15, 4
	s_add_i32 s15, s15, s16
	s_mul_i32 s17, s15, 0xffffea00
	s_add_i32 s18, s13, s17
	s_lshl_b32 s16, s15, 6
	s_ashr_i32 s19, s18, 31
	v_or_b32_e32 v15, s16, v8
	v_add_u32_e32 v17, s16, v9
	v_lshl_add_u64 v[18:19], s[18:19], 2, v[4:5]
	v_mad_i64_i32 v[20:21], s[20:21], v15, s11, v[18:19]
	v_mad_i64_i32 v[22:23], s[20:21], v17, s11, v[18:19]
	global_load_dwordx4 v[18:21], v[20:21], off nt
	s_nop 0
	global_load_dwordx4 v[22:25], v[22:23], off nt
	s_mulk_i32 s15, 0xd400
	v_add_u32_e32 v15, s15, v16
	v_add_u32_e32 v17, s18, v10
	v_and_b32_e32 v15, 0xffffff00, v15
	v_and_b32_e32 v17, 0x7f, v17
	v_or3_b32 v26, v17, v15, s12
	v_ashrrev_i32_e32 v27, 31, v26
	v_lshlrev_b64 v[26:27], 12, v[26:27]
	s_ashr_i32 s17, s16, 31
	v_lshl_add_u64 v[26:27], s[0:1], 0, v[26:27]
	s_add_i32 s14, s14, s3
	s_add_i32 s13, s13, s9
	v_lshl_add_u64 v[26:27], s[16:17], 1, v[26:27]
	v_add_u32_e32 v16, s10, v16
	s_cmpk_lt_i32 s14, 0xb00
	v_lshl_add_u64 v[26:27], v[26:27], 0, v[0:1]
	s_cselect_b32 s22, 1, 0
	s_waitcnt vmcnt(0)
	s_branch .Ltp5_body

; __device__ __forceinline__ u32x4 pack8(const float* v) { u32x4 w; w.x = cvt_pk_bf16(v[0], v[1]); w.y = cvt_pk_bf16(v[2], v[3]); w.z = cvt_pk_bf16(v[4], v[5]); w.w = cvt_pk_bf16(v[6], v[7]); return w; }
; __device__ __forceinline__ void transpose_tile(const float* W, int K, int N, bf16_t* Bt, int ldb, int mode, int tk, int tn, float* tile  ) {
;     ...
;       for (int hh = 0; hh < 2; ++hh) { const int rr = r + hh * 32; const f32x4 v = __builtin_nontemporal_load((const f32x4*)(W + (size_t)(tk * 64 + rr) * N + tn * 64 + c4));
;           tile[rr * 65 + c4] = v[0]; tile[rr * 65 + c4 + 1] = v[1]; tile[rr * 65 + c4 + 2] = v[2]; tile[rr * 65 + c4 + 3] = v[3]; } }
;     __syncthreads();
;     { const int n = tid >> 3, k8 = (tid & 7) * 8; float v[8];
; #pragma unroll
;       for (int j = 0; j < 8; ++j) v[j] = tile[(k8 + j) * 65 + n];
;       const int ng = tn * 64 + n; const int row = mode == 0 ? ng : ((ng >> 7) * 256 + (mode - 1) * 128 + (ng & 127));
;       *(u32x4*)(Bt + (size_t)row * ldb + tk * 64 + k8) = pack8(v); }
; __device__ void phase_prep(const Args& A, float* ldsf) {
;     ...
;         for (int t = blockIdx.x; t < ntile; t += gridDim.x) transpose_tile(jobs[j].W, jobs[j].K, jobs[j].N, jobs[j].Bt, jobs[j].ldb, jobs[j].mode, t / ntn, t % ntn, ldsf); }
.Ltp5_body:
	ds_write2_b32 v11, v18, v19 offset1:1
	ds_write2_b32 v11, v20, v21 offset0:2 offset1:3
	ds_write2_b32 v12, v22, v23 offset1:1
	ds_write2_b32 v14, v24, v25 offset1:1
	v_mov_b32_e32 v108, v26
	v_mov_b32_e32 v109, v27
	s_waitcnt lgkmcnt(0)
	s_barrier
	s_cmp_lg_u32 s22, 0
	s_cbranch_scc0 .Ltp5_nohead
	s_mul_hi_i32 s15, s14, 0x2e8ba2e9
	s_lshr_b32 s16, s15, 31
	s_ashr_i32 s15, s15, 4
	s_add_i32 s15, s15, s16
	s_mul_i32 s17, s15, 0xffffea00
	s_add_i32 s18, s13, s17
	s_lshl_b32 s16, s15, 6
	s_ashr_i32 s19, s18, 31
	v_or_b32_e32 v15, s16, v8
	v_add_u32_e32 v17, s16, v9
	v_lshl_add_u64 v[18:19], s[18:19], 2, v[4:5]
	v_mad_i64_i32 v[20:21], s[20:21], v15, s11, v[18:19]
	v_mad_i64_i32 v[22:23], s[20:21], v17, s11, v[18:19]
	global_load_dwordx4 v[18:21], v[20:21], off nt
	s_nop 0
	global_load_dwordx4 v[22:25], v[22:23], off nt
	s_mulk_i32 s15, 0xd400
	v_add_u32_e32 v15, s15, v16
	v_add_u32_e32 v17, s18, v10
	v_and_b32_e32 v15, 0xffffff00, v15
	v_and_b32_e32 v17, 0x7f, v17
	v_or3_b32 v26, v17, v15, s12
	v_ashrrev_i32_e32 v27, 31, v26
	v_lshlrev_b64 v[26:27], 12, v[26:27]
	s_ashr_i32 s17, s16, 31
	v_lshl_add_u64 v[26:27], s[0:1], 0, v[26:27]
	s_add_i32 s14, s14, s3
	s_add_i32 s13, s13, s9
	v_lshl_add_u64 v[26:27], s[16:17], 1, v[26:27]
	v_add_u32_e32 v16, s10, v16
	s_cmpk_lt_i32 s14, 0xb00
	v_lshl_add_u64 v[26:27], v[26:27], 0, v[0:1]
	s_cselect_b32 s23, 1, 0
	s_branch .Ltp5_tail

; __device__ __forceinline__ u32x4 pack8(const float* v) { u32x4 w; w.x = cvt_pk_bf16(v[0], v[1]); w.y = cvt_pk_bf16(v[2], v[3]); w.z = cvt_pk_bf16(v[4], v[5]); w.w = cvt_pk_bf16(v[6], v[7]); return w; }
; __device__ __forceinline__ void transpose_tile(const float* W, int K, int N, bf16_t* Bt, int ldb, int mode, int tk, int tn, float* tile  ) {
;     ...
;     __syncthreads();
;     { const int n = tid >> 3, k8 = (tid & 7) * 8; float v[8];
; #pragma unroll
;       for (int j = 0; j < 8; ++j) v[j] = tile[(k8 + j) * 65 + n];
;       const int ng = tn * 64 + n; const int row = mode == 0 ? ng : ((ng >> 7) * 256 + (mode - 1) * 128 + (ng & 127));
;       *(u32x4*)(Bt + (size_t)row * ldb + tk * 64 + k8) = pack8(v); }
; __device__ void phase_prep(const Args& A, float* ldsf) {
;     ...
;     for (int j = 0; j < 7; ++j) { const int ntk = jobs[j].K / 64, ntn = jobs[j].N / 64, ntile = ntk * ntn;
;         for (int t = blockIdx.x; t < ntile; t += gridDim.x) transpose_tile(jobs[j].W, jobs[j].K, jobs[j].N, jobs[j].Bt, jobs[j].ldb, jobs[j].mode, t / ntn, t % ntn, ldsf); }
.Ltp5_tail:
	ds_read2_b32 v[100:101], v13 offset1:65
	ds_read2_b32 v[102:103], v13 offset0:130 offset1:195
	ds_read2_b32 v[104:105], v3 offset0:4 offset1:69
	ds_read2_b32 v[106:107], v3 offset0:134 offset1:199
	s_waitcnt lgkmcnt(3)
	v_cvt_pk_bf16_f32 v100, v100, v101
	s_waitcnt lgkmcnt(2)
	v_cvt_pk_bf16_f32 v101, v102, v103
	s_waitcnt lgkmcnt(1)
	v_cvt_pk_bf16_f32 v102, v104, v105
	s_waitcnt lgkmcnt(0)
	v_cvt_pk_bf16_f32 v103, v106, v107
	global_store_dwordx4 v[108:109], v[100:103], off
	s_barrier
	s_cmp_lg_u32 s22, 0
	s_mov_b32 s22, s23
	s_cbranch_scc1 .Ltp5_top
	s_mul_i32 s10, s2, 0x58000
	s_add_u32 s0, s76, 0x6400000
	v_mov_b32_e32 v3, 0
	s_movk_i32 s11, 0x1600
	v_mov_b32_e32 v1, s10
	s_addc_u32 s1, s77, 0
	v_lshl_add_u64 v[4:5], s[72:73], 0, v[2:3]
	v_mad_u32_u24 v2, v10, s11, v1
	s_mul_i32 s10, s3, 0x58000
	v_add_u32_e32 v10, 0x2080, v11
	v_add_u32_e32 v12, 0x2088, v11
	v_mov_b32_e32 v1, v3
	v_add_u32_e32 v3, 0x400, v13
	s_mov_b32 s11, s2
.LBB0_35:
	s_ashr_i32 s12, s11, 31
	s_lshr_b32 s12, s12, 27
	s_add_i32 s12, s11, s12
	s_ashr_i32 s13, s12, 5
	s_lshl_b32 s12, s13, 6
	s_lshl_b32 s14, s13, 11
	s_sub_i32 s14, s8, s14
	v_or_b32_e32 v14, s12, v8
	v_add_u32_e32 v16, s12, v9
	s_ashr_i32 s15, s14, 31
	v_ashrrev_i32_e32 v15, 31, v14
	v_ashrrev_i32_e32 v17, 31, v16
	v_lshl_add_u64 v[18:19], s[14:15], 2, v[4:5]
	v_lshlrev_b64 v[14:15], 13, v[14:15]
	v_lshlrev_b64 v[16:17], 13, v[16:17]
	v_lshl_add_u64 v[22:23], v[18:19], 0, v[14:15]
	v_lshl_add_u64 v[24:25], v[18:19], 0, v[16:17]
	global_load_dwordx4 v[14:17], v[22:23], off nt
	global_load_dwordx4 v[18:21], v[24:25], off nt
	s_mul_i32 s13, s13, 0xff500000
	v_add_u32_e32 v22, s13, v2
	v_ashrrev_i32_e32 v23, 31, v22
	s_ashr_i32 s13, s12, 31
	v_lshl_add_u64 v[22:23], v[22:23], 1, s[0:1]
	s_add_i32 s11, s11, s3
	s_add_i32 s8, s8, s9
	v_lshl_add_u64 v[22:23], s[12:13], 1, v[22:23]
	v_add_u32_e32 v2, s10, v2
	s_cmpk_lt_i32 s11, 0xb00
	v_lshl_add_u64 v[22:23], v[22:23], 0, v[0:1]
	s_cselect_b32 s22, 1, 0
	s_waitcnt vmcnt(0)
	s_branch .Ltp6_body

; __device__ __forceinline__ u32x4 pack8(const float* v) { u32x4 w; w.x = cvt_pk_bf16(v[0], v[1]); w.y = cvt_pk_bf16(v[2], v[3]); w.z = cvt_pk_bf16(v[4], v[5]); w.w = cvt_pk_bf16(v[6], v[7]); return w; }
; __device__ __forceinline__ void transpose_tile(const float* W, int K, int N, bf16_t* Bt, int ldb, int mode, int tk, int tn, float* tile  ) {
;     ...
;       for (int hh = 0; hh < 2; ++hh) { const int rr = r + hh * 32; const f32x4 v = __builtin_nontemporal_load((const f32x4*)(W + (size_t)(tk * 64 + rr) * N + tn * 64 + c4));
;           tile[rr * 65 + c4] = v[0]; tile[rr * 65 + c4 + 1] = v[1]; tile[rr * 65 + c4 + 2] = v[2]; tile[rr * 65 + c4 + 3] = v[3]; } }
;     __syncthreads();
;     { const int n = tid >> 3, k8 = (tid & 7) * 8; float v[8];
; #pragma unroll
;       for (int j = 0; j < 8; ++j) v[j] = tile[(k8 + j) * 65 + n];
;       const int ng = tn * 64 + n; const int row = mode == 0 ? ng : ((ng >> 7) * 256 + (mode - 1) * 128 + (ng & 127));
;       *(u32x4*)(Bt + (size_t)row * ldb + tk * 64 + k8) = pack8(v); }
; __device__ void phase_prep(const Args& A, float* ldsf) {
;     ...
;         for (int t = blockIdx.x; t < ntile; t += gridDim.x) transpose_tile(jobs[j].W, jobs[j].K, jobs[j].N, jobs[j].Bt, jobs[j].ldb, jobs[j].mode, t / ntn, t % ntn, ldsf); }
.Ltp6_body:
	ds_write2_b32 v11, v14, v15 offset1:1
	ds_write2_b32 v11, v16, v17 offset0:2 offset1:3
	ds_write2_b32 v10, v18, v19 offset1:1
	ds_write2_b32 v12, v20, v21 offset1:1
	v_mov_b32_e32 v108, v22
	v_mov_b32_e32 v109, v23
	s_waitcnt lgkmcnt(0)
	s_barrier
	s_cmp_lg_u32 s22, 0
	s_cbranch_scc0 .Ltp6_nohead
	s_ashr_i32 s12, s11, 31
	s_lshr_b32 s12, s12, 27
	s_add_i32 s12, s11, s12
	s_ashr_i32 s13, s12, 5
	s_lshl_b32 s12, s13, 6
	s_lshl_b32 s14, s13, 11
	s_sub_i32 s14, s8, s14
	v_or_b32_e32 v14, s12, v8
	v_add_u32_e32 v16, s12, v9
	s_ashr_i32 s15, s14, 31
	v_ashrrev_i32_e32 v15, 31, v14
	v_ashrrev_i32_e32 v17, 31, v16
	v_lshl_add_u64 v[18:19], s[14:15], 2, v[4:5]
	v_lshlrev_b64 v[14:15], 13, v[14:15]
	v_lshlrev_b64 v[16:17], 13, v[16:17]
	v_lshl_add_u64 v[22:23], v[18:19], 0, v[14:15]
	v_lshl_add_u64 v[24:25], v[18:19], 0, v[16:17]
	global_load_dwordx4 v[14:17], v[22:23], off nt
	global_load_dwordx4 v[18:21], v[24:25], off nt
	s_mul_i32 s13, s13, 0xff500000
	v_add_u32_e32 v22, s13, v2
	v_ashrrev_i32_e32 v23, 31, v22
	s_ashr_i32 s13, s12, 31
	v_lshl_add_u64 v[22:23], v[22:23], 1, s[0:1]
	s_add_i32 s11, s11, s3
	s_add_i32 s8, s8, s9
	v_lshl_add_u64 v[22:23], s[12:13], 1, v[22:23]
	v_add_u32_e32 v2, s10, v2
	s_cmpk_lt_i32 s11, 0xb00
	v_lshl_add_u64 v[22:23], v[22:23], 0, v[0:1]
	s_cselect_b32 s23, 1, 0
	s_branch .Ltp6_tail

; __device__ __forceinline__ u32x4 pack8(const float* v) { u32x4 w; w.x = cvt_pk_bf16(v[0], v[1]); w.y = cvt_pk_bf16(v[2], v[3]); w.z = cvt_pk_bf16(v[4], v[5]); w.w = cvt_pk_bf16(v[6], v[7]); return w; }
; __device__ __forceinline__ void transpose_tile(const float* W, int K, int N, bf16_t* Bt, int ldb, int mode, int tk, int tn, float* tile  ) {
;     ...
;     __syncthreads();
;     { const int n = tid >> 3, k8 = (tid & 7) * 8; float v[8];
; #pragma unroll
;       for (int j = 0; j < 8; ++j) v[j] = tile[(k8 + j) * 65 + n];
;       const int ng = tn * 64 + n; const int row = mode == 0 ? ng : ((ng >> 7) * 256 + (mode - 1) * 128 + (ng & 127));
;       *(u32x4*)(Bt + (size_t)row * ldb + tk * 64 + k8) = pack8(v); }
; __device__ void phase_prep(const Args& A, float* ldsf) {
;     ...
;     for (int j = 0; j < 7; ++j) { const int ntk = jobs[j].K / 64, ntn = jobs[j].N / 64, ntile = ntk * ntn;
;         for (int t = blockIdx.x; t < ntile; t += gridDim.x) transpose_tile(jobs[j].W, jobs[j].K, jobs[j].N, jobs[j].Bt, jobs[j].ldb, jobs[j].mode, t / ntn, t % ntn, ldsf); }
.Ltp6_tail:
	ds_read2_b32 v[100:101], v13 offset1:65
	ds_read2_b32 v[102:103], v13 offset0:130 offset1:195
	ds_read2_b32 v[104:105], v3 offset0:4 offset1:69
	ds_read2_b32 v[106:107], v3 offset0:134 offset1:199
	s_waitcnt lgkmcnt(3)
	v_cvt_pk_bf16_f32 v100, v100, v101
	s_waitcnt lgkmcnt(2)
	v_cvt_pk_bf16_f32 v101, v102, v103
	s_waitcnt lgkmcnt(1)
	v_cvt_pk_bf16_f32 v102, v104, v105
	s_waitcnt lgkmcnt(0)
	v_cvt_pk_bf16_f32 v103, v106, v107
	global_store_dwordx4 v[108:109], v[100:103], off
	s_barrier
	s_cmp_lg_u32 s22, 0
	s_mov_b32 s22, s23
	s_cbranch_scc1 .Ltp6_top
